# K fragment reads up front in S1 combined with prio S1 raise + S2 hand schedule + ccdma + P0 transposes MLP
# baseline (speedup 1.0000x reference)
; #define MFMA32(a, b, c) __builtin_amdgcn_mfma_f32_32x32x16_bf16((a), (b), (c), 0, 0, 0)
; DI void attn_unit(const Params& p, int bh, int qb, char* lds, float lam, int tid, int lane, int wid, const bool build_tab) {
;     ...
;             const lds_cptr kp = (lds_cptr)lds + sc + map * 8192 + hi * 1024 + r32 * 16;
;             bf16x8 kf[8];
; #pragma unroll
;             for (int d0 = 0; d0 < 4; ++d0) {
;                 kf[2 * d0] = *(const __attribute__((address_space(3))) bf16x8*)(kp + d0 * 2048);
;                 kf[2 * d0 + 1] = *(const __attribute__((address_space(3))) bf16x8*)(kp + d0 * 2048 + 512);
;             }
;             f32x16 s0 = cinit, s1 = cinit;
; #pragma unroll
;             for (int d0 = 0; d0 < 4; ++d0) { s0 = MFMA32(kf[2 * d0], qf[d0], s0); s1 = MFMA32(kf[2 * d0 + 1], qf[d0], s1); }
.Lp3_1:
	s_add_i32 s50, s84, 0
	s_add_i32 s51, s50, s61
	v_add3_u32 v221, s51, v204, v205
	ds_read_b128 v[128:131], v221
	ds_read_b128 v[222:225], v221 offset:512
	ds_read_b128 v[132:135], v221 offset:2048
	ds_read_b128 v[226:229], v221 offset:2560
	ds_read_b128 v[136:139], v221 offset:4096
	ds_read_b128 v[230:233], v221 offset:4608
	ds_read_b128 v[140:143], v221 offset:6144
	ds_read_b128 v[234:237], v221 offset:6656
	s_cmp_lt_u32 s7, s79
	v_add3_u32 v220, s50, v171, v202
	v_add_u32_e32 v220, v220, v203
	s_waitcnt lgkmcnt(7)
	v_mfma_f32_32x32x16_bf16 v[96:111], v[128:131], v[112:115], v[64:79]
	s_waitcnt lgkmcnt(6)
	v_mfma_f32_32x32x16_bf16 v[80:95], v[222:225], v[112:115], v[64:79]
	s_waitcnt lgkmcnt(5)
	v_mfma_f32_32x32x16_bf16 v[96:111], v[132:135], v[116:119], v[96:111]
	s_waitcnt lgkmcnt(4)
	v_mfma_f32_32x32x16_bf16 v[80:95], v[226:229], v[116:119], v[80:95]
	s_waitcnt lgkmcnt(3)
	v_mfma_f32_32x32x16_bf16 v[96:111], v[136:139], v[120:123], v[96:111]
	s_waitcnt lgkmcnt(2)
	v_mfma_f32_32x32x16_bf16 v[80:95], v[230:233], v[120:123], v[80:95]
	s_waitcnt lgkmcnt(1)
	v_mfma_f32_32x32x16_bf16 v[96:111], v[140:143], v[124:127], v[96:111]
	ds_read_b64_tr_b16 v[140:141], v220 offset:16384
	ds_read_b64_tr_b16 v[142:143], v220 offset:16896
	ds_read_b64_tr_b16 v[136:137], v220 offset:20480
	ds_read_b64_tr_b16 v[138:139], v220 offset:20992
	ds_read_b64_tr_b16 v[132:133], v220 offset:24576
	ds_read_b64_tr_b16 v[134:135], v220 offset:25088
	ds_read_b64_tr_b16 v[128:129], v220 offset:28672
	ds_read_b64_tr_b16 v[130:131], v220 offset:29184
	s_waitcnt lgkmcnt(8)
	v_mfma_f32_32x32x16_bf16 v[80:95], v[234:237], v[124:127], v[80:95]
	s_cbranch_scc1 .LBB0_355
	v_add_u32_e32 v221, s83, v219
	v_add_u32_e32 v222, 0x18600, v221
	v_add_u32_e32 v224, 0x18680, v221
	v_add_u32_e32 v226, 0x18608, v221
	v_add_u32_e32 v228, 0x18688, v221
	v_add_u32_e32 v230, 0x18620, v221
	v_add_u32_e32 v232, 0x186a0, v221
	v_add_u32_e32 v234, 0x18628, v221
	v_add_u32_e32 v236, 0x186a8, v221
	v_add_u32_e32 v238, 0x18640, v221
	v_add_u32_e32 v240, 0x186c0, v221
	v_add_u32_e32 v242, 0x18648, v221
	v_add_u32_e32 v244, 0x186c8, v221
	v_add_u32_e32 v248, 0x18660, v221
	v_add_u32_e32 v250, 0x186e0, v221
	v_add_u32_e32 v246, 0x18668, v221
	ds_read2_b32 v[222:223], v222 offset1:1
	ds_read2_b32 v[224:225], v224 offset1:1
	ds_read2_b32 v[226:227], v226 offset1:1
	ds_read2_b32 v[228:229], v228 offset1:1
	ds_read2_b32 v[230:231], v230 offset1:1
	ds_read2_b32 v[232:233], v232 offset1:1
	ds_read2_b32 v[234:235], v234 offset1:1
	ds_read2_b32 v[236:237], v236 offset1:1
	ds_read2_b32 v[238:239], v238 offset1:1
	ds_read2_b32 v[240:241], v240 offset1:1
	ds_read2_b32 v[242:243], v242 offset1:1
	ds_read2_b32 v[244:245], v244 offset1:1
	ds_read2_b32 v[246:247], v246 offset1:1
	ds_read2_b32 v[248:249], v248 offset1:1
	v_add_u32_e32 v221, 0x186e8, v221
	ds_read2_b32 v[250:251], v250 offset1:1
	ds_read2_b32 v[252:253], v221 offset1:1
	s_waitcnt lgkmcnt(5)
	v_pk_add_f32 v[106:107], v[106:107], v[242:243]
	s_waitcnt lgkmcnt(3)
	v_pk_add_f32 v[110:111], v[110:111], v[246:247]
	s_waitcnt lgkmcnt(2)
	v_pk_add_f32 v[108:109], v[108:109], v[248:249]
	v_pk_add_f32 v[104:105], v[104:105], v[238:239]
	v_pk_add_f32 v[102:103], v[102:103], v[234:235]
	v_pk_add_f32 v[100:101], v[100:101], v[230:231]
	v_pk_add_f32 v[98:99], v[98:99], v[226:227]
	v_pk_add_f32 v[96:97], v[96:97], v[222:223]
	s_waitcnt lgkmcnt(0)
	v_pk_add_f32 v[94:95], v[94:95], v[252:253]
	v_pk_add_f32 v[92:93], v[92:93], v[250:251]
	v_pk_add_f32 v[90:91], v[90:91], v[244:245]
	v_pk_add_f32 v[88:89], v[88:89], v[240:241]
	v_pk_add_f32 v[86:87], v[86:87], v[236:237]
	v_pk_add_f32 v[84:85], v[84:85], v[232:233]
	v_pk_add_f32 v[82:83], v[82:83], v[228:229]
	v_pk_add_f32 v[80:81], v[80:81], v[224:225]

; #define MFMA32(a, b, c) __builtin_amdgcn_mfma_f32_32x32x16_bf16((a), (b), (c), 0, 0, 0)
; DI void attn_unit(const Params& p, int bh, int qb, char* lds, float lam, int tid, int lane, int wid, const bool build_tab) {
;     ...
;             const lds_cptr kp = (lds_cptr)lds + sc + map * 8192 + hi * 1024 + r32 * 16;
;             bf16x8 kf[8];
; #pragma unroll
;             for (int d0 = 0; d0 < 4; ++d0) {
;                 kf[2 * d0] = *(const __attribute__((address_space(3))) bf16x8*)(kp + d0 * 2048);
;                 kf[2 * d0 + 1] = *(const __attribute__((address_space(3))) bf16x8*)(kp + d0 * 2048 + 512);
;             }
;             f32x16 s0 = cinit, s1 = cinit;
; #pragma unroll
;             for (int d0 = 0; d0 < 4; ++d0) { s0 = MFMA32(kf[2 * d0], qf[d0], s0); s1 = MFMA32(kf[2 * d0 + 1], qf[d0], s1); }
.Lp3_0:
	s_add_i32 s52, s70, 0
	s_add_i32 s53, s52, s61
	v_add3_u32 v244, s53, v204, v205
	ds_read_b128 v[128:131], v244
	ds_read_b128 v[178:181], v244 offset:512
	ds_read_b128 v[132:135], v244 offset:2048
	ds_read_b128 v[182:185], v244 offset:2560
	ds_read_b128 v[136:139], v244 offset:4096
	ds_read_b128 v[186:189], v244 offset:4608
	ds_read_b128 v[140:143], v244 offset:6144
	ds_read_b128 v[190:193], v244 offset:6656
	s_cmp_lt_i32 s51, s57
	v_add3_u32 v177, s52, v171, v202
	v_add_u32_e32 v177, v177, v203
	s_waitcnt lgkmcnt(7)
	v_mfma_f32_32x32x16_bf16 v[96:111], v[128:131], v[112:115], v[64:79]
	s_waitcnt lgkmcnt(6)
	v_mfma_f32_32x32x16_bf16 v[80:95], v[178:181], v[112:115], v[64:79]
	s_waitcnt lgkmcnt(5)
	v_mfma_f32_32x32x16_bf16 v[96:111], v[132:135], v[116:119], v[96:111]
	s_waitcnt lgkmcnt(4)
	v_mfma_f32_32x32x16_bf16 v[80:95], v[182:185], v[116:119], v[80:95]
	s_waitcnt lgkmcnt(3)
	v_mfma_f32_32x32x16_bf16 v[96:111], v[136:139], v[120:123], v[96:111]
	s_waitcnt lgkmcnt(2)
	v_mfma_f32_32x32x16_bf16 v[80:95], v[186:189], v[120:123], v[80:95]
	s_waitcnt lgkmcnt(1)
	v_mfma_f32_32x32x16_bf16 v[96:111], v[140:143], v[124:127], v[96:111]
	ds_read_b64_tr_b16 v[140:141], v177 offset:16384
	ds_read_b64_tr_b16 v[142:143], v177 offset:16896
	ds_read_b64_tr_b16 v[136:137], v177 offset:20480
	ds_read_b64_tr_b16 v[138:139], v177 offset:20992
	ds_read_b64_tr_b16 v[132:133], v177 offset:24576
	ds_read_b64_tr_b16 v[134:135], v177 offset:25088
	ds_read_b64_tr_b16 v[128:129], v177 offset:28672
	ds_read_b64_tr_b16 v[130:131], v177 offset:29184
	s_waitcnt lgkmcnt(8)
	v_mfma_f32_32x32x16_bf16 v[80:95], v[190:193], v[124:127], v[80:95]
	s_cbranch_scc1 .LBB0_375
	v_add_u32_e32 v219, s69, v146
	v_add_u32_e32 v178, 0x18600, v219
	v_add_u32_e32 v180, 0x18680, v219
	v_add_u32_e32 v182, 0x18608, v219
	v_add_u32_e32 v184, 0x18688, v219
	v_add_u32_e32 v186, 0x18620, v219
	v_add_u32_e32 v188, 0x186a0, v219
	v_add_u32_e32 v190, 0x18628, v219
	v_add_u32_e32 v192, 0x186a8, v219
	v_add_u32_e32 v194, 0x18640, v219
	v_add_u32_e32 v196, 0x186c0, v219
	v_add_u32_e32 v198, 0x18648, v219
	v_add_u32_e32 v220, 0x186c8, v219
	v_add_u32_e32 v224, 0x18660, v219
	v_add_u32_e32 v226, 0x186e0, v219
	v_add_u32_e32 v222, 0x18668, v219
	ds_read2_b32 v[178:179], v178 offset1:1
	ds_read2_b32 v[180:181], v180 offset1:1
	ds_read2_b32 v[182:183], v182 offset1:1
	ds_read2_b32 v[184:185], v184 offset1:1
	ds_read2_b32 v[186:187], v186 offset1:1
	ds_read2_b32 v[188:189], v188 offset1:1
	ds_read2_b32 v[190:191], v190 offset1:1
	ds_read2_b32 v[192:193], v192 offset1:1
	ds_read2_b32 v[194:195], v194 offset1:1
	ds_read2_b32 v[196:197], v196 offset1:1
	ds_read2_b32 v[198:199], v198 offset1:1
	ds_read2_b32 v[220:221], v220 offset1:1
	ds_read2_b32 v[222:223], v222 offset1:1
	ds_read2_b32 v[224:225], v224 offset1:1
	v_add_u32_e32 v219, 0x186e8, v219
	ds_read2_b32 v[226:227], v226 offset1:1
	ds_read2_b32 v[228:229], v219 offset1:1
	s_waitcnt lgkmcnt(5)
	v_pk_add_f32 v[106:107], v[106:107], v[198:199]
	s_waitcnt lgkmcnt(3)
	v_pk_add_f32 v[110:111], v[110:111], v[222:223]
	s_waitcnt lgkmcnt(2)
	v_pk_add_f32 v[108:109], v[108:109], v[224:225]
	v_pk_add_f32 v[104:105], v[104:105], v[194:195]
	v_pk_add_f32 v[102:103], v[102:103], v[190:191]
	v_pk_add_f32 v[100:101], v[100:101], v[186:187]
	v_pk_add_f32 v[98:99], v[98:99], v[182:183]
	v_pk_add_f32 v[96:97], v[96:97], v[178:179]
	s_waitcnt lgkmcnt(0)
	v_pk_add_f32 v[94:95], v[94:95], v[228:229]
	v_pk_add_f32 v[92:93], v[92:93], v[226:227]
	v_pk_add_f32 v[90:91], v[90:91], v[220:221]
	v_pk_add_f32 v[88:89], v[88:89], v[196:197]
	v_pk_add_f32 v[86:87], v[86:87], v[192:193]
	v_pk_add_f32 v[84:85], v[84:85], v[188:189]
	v_pk_add_f32 v[82:83], v[82:83], v[184:185]
	v_pk_add_f32 v[80:81], v[80:81], v[180:181]
